# indexer select: borrow-bit arithmetic compares in VGPRs (no SGPR-writing VALU in the chain), only existing key blocks compared (entry ladder)
# baseline (speedup 1.0000x reference)
; DI void indexer_phase(const u16* __restrict__ P, unsigned* __restrict__ mask) {
;     ...
;     const int target = (tme + 1 < 256) ? tme + 1 : 256;
;     unsigned T = 0u;
;     ...
;       const unsigned Tp = T | (1u << bit);
;       int cnt = 0;
; #pragma unroll
;       for (int kb = 0; kb < 64; ++kb) cnt += (sc[kb] >= Tp) ? 1 : 0;
; #pragma unroll
;       for (int o = 16; o; o >>= 1) cnt += __shfl_xor(cnt, o);
;       if (cnt >= target) T = Tp;
;     }
.Lix_done:
	s_mov_b32 s63, s3
	s_mov_b32 s79, s84
	s_mov_b64 s[84:85], s[4:5]
	s_mov_b32 s59, s55
	s_mov_b32 s78, s28
	s_mov_b32 s86, s35
	s_mov_b64 s[16:17], s[90:91]
	s_mov_b64 s[96:97], s[52:53]
	s_mov_b64 s[76:77], s[42:43]
	v_mov_b32_e32 v144, 0
	s_mov_b32 s0, 31
	v_min_i32_e32 v3, 0xff, v127
	v_readfirstlane_b32 s2, v127
	s_nop 0
	s_add_i32 s2, s2, 1
	s_lshr_b32 s2, s2, 8
	s_lshl_b32 s72, s2, 3
	s_add_i32 s72, s72, 8
	v_cmp_lt_i32_e32 vcc, v221, v248
	s_nop 1
	v_cndmask_b32_e32 v4, v234, v221, vcc
	v_cmp_lt_i32_e32 vcc, v220, v248
	v_lshlrev_b32_e32 v4, 2, v4
	s_nop 0
	v_cndmask_b32_e32 v5, v234, v220, vcc
	v_cmp_lt_i32_e32 vcc, v219, v248
	v_lshlrev_b32_e32 v5, 2, v5
	s_nop 0
	v_cndmask_b32_e32 v6, v234, v219, vcc
	v_cmp_lt_i32_e32 vcc, v218, v248
	v_lshlrev_b32_e32 v6, 2, v6
	s_nop 0
	v_cndmask_b32_e32 v7, v234, v218, vcc
	v_cmp_lt_i32_e32 vcc, v249, v248
	v_lshlrev_b32_e32 v7, 2, v7
	s_nop 0
	v_cndmask_b32_e32 v8, v234, v249, vcc
	v_lshlrev_b32_e32 v8, 2, v8
.LBB0_974:
	s_lshl_b32 s1, 1, s0
	v_or_b32_e32 v9, s1, v144
	s_add_i32 s0, s0, -1
	v_mov_b32_e32 v10, 0
	v_mov_b32_e32 v11, 0
	s_cmp_eq_u32 s2, 7
	s_cbranch_scc1 .Lsel_g7
	s_cmp_eq_u32 s2, 6
	s_cbranch_scc1 .Lsel_g6
	s_cmp_eq_u32 s2, 5
	s_cbranch_scc1 .Lsel_g5
	s_cmp_eq_u32 s2, 4
	s_cbranch_scc1 .Lsel_g4
	s_cmp_eq_u32 s2, 3
	s_cbranch_scc1 .Lsel_g3
	s_cmp_eq_u32 s2, 2
	s_cbranch_scc1 .Lsel_g2
	s_cmp_eq_u32 s2, 1
	s_cbranch_scc1 .Lsel_g1
	s_branch .Lsel_g0
.Lsel_g7:
	v_sub_u32_e32 v12, v205, v9
	v_sub_u32_e32 v13, v236, v9
	v_sub_u32_e32 v14, v207, v9
	v_sub_u32_e32 v15, v238, v9
	v_bitop3_b32 v12, v205, v9, v12 bitop3:0x8e
	v_bitop3_b32 v13, v236, v9, v13 bitop3:0x8e
	v_bitop3_b32 v14, v207, v9, v14 bitop3:0x8e
	v_bitop3_b32 v15, v238, v9, v15 bitop3:0x8e
	v_lshrrev_b32_e32 v12, 31, v12
	v_lshrrev_b32_e32 v13, 31, v13
	v_lshrrev_b32_e32 v14, 31, v14
	v_lshrrev_b32_e32 v15, 31, v15
	v_add3_u32 v10, v10, v12, v13
	v_add3_u32 v11, v11, v14, v15
	v_sub_u32_e32 v12, v237, v9
	v_sub_u32_e32 v13, v240, v9
	v_sub_u32_e32 v14, v239, v9
	v_sub_u32_e32 v15, v18, v9
	v_bitop3_b32 v12, v237, v9, v12 bitop3:0x8e
	v_bitop3_b32 v13, v240, v9, v13 bitop3:0x8e
	v_bitop3_b32 v14, v239, v9, v14 bitop3:0x8e
	v_bitop3_b32 v15, v18, v9, v15 bitop3:0x8e
	v_lshrrev_b32_e32 v12, 31, v12
	v_lshrrev_b32_e32 v13, 31, v13
	v_lshrrev_b32_e32 v14, 31, v14
	v_lshrrev_b32_e32 v15, 31, v15
	v_add3_u32 v10, v10, v12, v13
	v_add3_u32 v11, v11, v14, v15
.Lsel_g6:
	v_sub_u32_e32 v12, v197, v9
	v_sub_u32_e32 v13, v200, v9
	v_sub_u32_e32 v14, v199, v9
	v_sub_u32_e32 v15, v202, v9
	v_bitop3_b32 v12, v197, v9, v12 bitop3:0x8e
	v_bitop3_b32 v13, v200, v9, v13 bitop3:0x8e
	v_bitop3_b32 v14, v199, v9, v14 bitop3:0x8e
	v_bitop3_b32 v15, v202, v9, v15 bitop3:0x8e
	v_lshrrev_b32_e32 v12, 31, v12
	v_lshrrev_b32_e32 v13, 31, v13
	v_lshrrev_b32_e32 v14, 31, v14
	v_lshrrev_b32_e32 v15, 31, v15
	v_add3_u32 v10, v10, v12, v13
	v_add3_u32 v11, v11, v14, v15
	v_sub_u32_e32 v12, v201, v9
	v_sub_u32_e32 v13, v204, v9
	v_sub_u32_e32 v14, v203, v9
	v_sub_u32_e32 v15, v206, v9
	v_bitop3_b32 v12, v201, v9, v12 bitop3:0x8e
	v_bitop3_b32 v13, v204, v9, v13 bitop3:0x8e
	v_bitop3_b32 v14, v203, v9, v14 bitop3:0x8e
	v_bitop3_b32 v15, v206, v9, v15 bitop3:0x8e
	v_lshrrev_b32_e32 v12, 31, v12
	v_lshrrev_b32_e32 v13, 31, v13
	v_lshrrev_b32_e32 v14, 31, v14
	v_lshrrev_b32_e32 v15, 31, v15
	v_add3_u32 v10, v10, v12, v13
	v_add3_u32 v11, v11, v14, v15
.Lsel_g5:
	v_sub_u32_e32 v12, v189, v9
	v_sub_u32_e32 v13, v192, v9
	v_sub_u32_e32 v14, v191, v9
	v_sub_u32_e32 v15, v194, v9
	v_bitop3_b32 v12, v189, v9, v12 bitop3:0x8e
	v_bitop3_b32 v13, v192, v9, v13 bitop3:0x8e
	v_bitop3_b32 v14, v191, v9, v14 bitop3:0x8e
	v_bitop3_b32 v15, v194, v9, v15 bitop3:0x8e
	v_lshrrev_b32_e32 v12, 31, v12
	v_lshrrev_b32_e32 v13, 31, v13
	v_lshrrev_b32_e32 v14, 31, v14
	v_lshrrev_b32_e32 v15, 31, v15
	v_add3_u32 v10, v10, v12, v13
	v_add3_u32 v11, v11, v14, v15
	v_sub_u32_e32 v12, v193, v9
	v_sub_u32_e32 v13, v196, v9
	v_sub_u32_e32 v14, v195, v9
	v_sub_u32_e32 v15, v198, v9
	v_bitop3_b32 v12, v193, v9, v12 bitop3:0x8e
	v_bitop3_b32 v13, v196, v9, v13 bitop3:0x8e
	v_bitop3_b32 v14, v195, v9, v14 bitop3:0x8e
	v_bitop3_b32 v15, v198, v9, v15 bitop3:0x8e
	v_lshrrev_b32_e32 v12, 31, v12
	v_lshrrev_b32_e32 v13, 31, v13
	v_lshrrev_b32_e32 v14, 31, v14
	v_lshrrev_b32_e32 v15, 31, v15
	v_add3_u32 v10, v10, v12, v13
	v_add3_u32 v11, v11, v14, v15
.Lsel_g4:
	v_sub_u32_e32 v12, v175, v9
	v_sub_u32_e32 v13, v184, v9
	v_sub_u32_e32 v14, v183, v9
	v_sub_u32_e32 v15, v186, v9
	v_bitop3_b32 v12, v175, v9, v12 bitop3:0x8e
	v_bitop3_b32 v13, v184, v9, v13 bitop3:0x8e
	v_bitop3_b32 v14, v183, v9, v14 bitop3:0x8e
	v_bitop3_b32 v15, v186, v9, v15 bitop3:0x8e
	v_lshrrev_b32_e32 v12, 31, v12
	v_lshrrev_b32_e32 v13, 31, v13
	v_lshrrev_b32_e32 v14, 31, v14
	v_lshrrev_b32_e32 v15, 31, v15
	v_add3_u32 v10, v10, v12, v13
	v_add3_u32 v11, v11, v14, v15
	v_sub_u32_e32 v12, v185, v9
	v_sub_u32_e32 v13, v188, v9
	v_sub_u32_e32 v14, v187, v9
	v_sub_u32_e32 v15, v190, v9
	v_bitop3_b32 v12, v185, v9, v12 bitop3:0x8e
	v_bitop3_b32 v13, v188, v9, v13 bitop3:0x8e
	v_bitop3_b32 v14, v187, v9, v14 bitop3:0x8e
	v_bitop3_b32 v15, v190, v9, v15 bitop3:0x8e
	v_lshrrev_b32_e32 v12, 31, v12
	v_lshrrev_b32_e32 v13, 31, v13
	v_lshrrev_b32_e32 v14, 31, v14
	v_lshrrev_b32_e32 v15, 31, v15
	v_add3_u32 v10, v10, v12, v13
	v_add3_u32 v11, v11, v14, v15
; DI void indexer_phase(const u16* __restrict__ P, unsigned* __restrict__ mask) {
;     ...
;       const unsigned Tp = T | (1u << bit);
;       int cnt = 0;
; #pragma unroll
;       for (int kb = 0; kb < 64; ++kb) cnt += (sc[kb] >= Tp) ? 1 : 0;
; #pragma unroll
;       for (int o = 16; o; o >>= 1) cnt += __shfl_xor(cnt, o);
;       if (cnt >= target) T = Tp;
;     }
.Lsel_g3:
	v_sub_u32_e32 v12, v167, v9
	v_sub_u32_e32 v13, v170, v9
	v_sub_u32_e32 v14, v169, v9
	v_sub_u32_e32 v15, v172, v9
	v_bitop3_b32 v12, v167, v9, v12 bitop3:0x8e
	v_bitop3_b32 v13, v170, v9, v13 bitop3:0x8e
	v_bitop3_b32 v14, v169, v9, v14 bitop3:0x8e
	v_bitop3_b32 v15, v172, v9, v15 bitop3:0x8e
	v_lshrrev_b32_e32 v12, 31, v12
	v_lshrrev_b32_e32 v13, 31, v13
	v_lshrrev_b32_e32 v14, 31, v14
	v_lshrrev_b32_e32 v15, 31, v15
	v_add3_u32 v10, v10, v12, v13
	v_add3_u32 v11, v11, v14, v15
	v_sub_u32_e32 v12, v171, v9
	v_sub_u32_e32 v13, v174, v9
	v_sub_u32_e32 v14, v173, v9
	v_sub_u32_e32 v15, v182, v9
	v_bitop3_b32 v12, v171, v9, v12 bitop3:0x8e
	v_bitop3_b32 v13, v174, v9, v13 bitop3:0x8e
	v_bitop3_b32 v14, v173, v9, v14 bitop3:0x8e
	v_bitop3_b32 v15, v182, v9, v15 bitop3:0x8e
	v_lshrrev_b32_e32 v12, 31, v12
	v_lshrrev_b32_e32 v13, 31, v13
	v_lshrrev_b32_e32 v14, 31, v14
	v_lshrrev_b32_e32 v15, 31, v15
	v_add3_u32 v10, v10, v12, v13
	v_add3_u32 v11, v11, v14, v15
.Lsel_g2:
	v_sub_u32_e32 v12, v159, v9
	v_sub_u32_e32 v13, v162, v9
	v_sub_u32_e32 v14, v161, v9
	v_sub_u32_e32 v15, v164, v9
	v_bitop3_b32 v12, v159, v9, v12 bitop3:0x8e
	v_bitop3_b32 v13, v162, v9, v13 bitop3:0x8e
	v_bitop3_b32 v14, v161, v9, v14 bitop3:0x8e
	v_bitop3_b32 v15, v164, v9, v15 bitop3:0x8e
	v_lshrrev_b32_e32 v12, 31, v12
	v_lshrrev_b32_e32 v13, 31, v13
	v_lshrrev_b32_e32 v14, 31, v14
	v_lshrrev_b32_e32 v15, 31, v15
	v_add3_u32 v10, v10, v12, v13
	v_add3_u32 v11, v11, v14, v15
	v_sub_u32_e32 v12, v163, v9
	v_sub_u32_e32 v13, v166, v9
	v_sub_u32_e32 v14, v165, v9
	v_sub_u32_e32 v15, v168, v9
	v_bitop3_b32 v12, v163, v9, v12 bitop3:0x8e
	v_bitop3_b32 v13, v166, v9, v13 bitop3:0x8e
	v_bitop3_b32 v14, v165, v9, v14 bitop3:0x8e
	v_bitop3_b32 v15, v168, v9, v15 bitop3:0x8e
	v_lshrrev_b32_e32 v12, 31, v12
	v_lshrrev_b32_e32 v13, 31, v13
	v_lshrrev_b32_e32 v14, 31, v14
	v_lshrrev_b32_e32 v15, 31, v15
	v_add3_u32 v10, v10, v12, v13
	v_add3_u32 v11, v11, v14, v15
.Lsel_g1:
	v_sub_u32_e32 v12, v151, v9
	v_sub_u32_e32 v13, v154, v9
	v_sub_u32_e32 v14, v153, v9
	v_sub_u32_e32 v15, v156, v9
	v_bitop3_b32 v12, v151, v9, v12 bitop3:0x8e
	v_bitop3_b32 v13, v154, v9, v13 bitop3:0x8e
	v_bitop3_b32 v14, v153, v9, v14 bitop3:0x8e
	v_bitop3_b32 v15, v156, v9, v15 bitop3:0x8e
	v_lshrrev_b32_e32 v12, 31, v12
	v_lshrrev_b32_e32 v13, 31, v13
	v_lshrrev_b32_e32 v14, 31, v14
	v_lshrrev_b32_e32 v15, 31, v15
	v_add3_u32 v10, v10, v12, v13
	v_add3_u32 v11, v11, v14, v15
	v_sub_u32_e32 v12, v155, v9
	v_sub_u32_e32 v13, v158, v9
	v_sub_u32_e32 v14, v157, v9
	v_sub_u32_e32 v15, v160, v9
	v_bitop3_b32 v12, v155, v9, v12 bitop3:0x8e
	v_bitop3_b32 v13, v158, v9, v13 bitop3:0x8e
	v_bitop3_b32 v14, v157, v9, v14 bitop3:0x8e
	v_bitop3_b32 v15, v160, v9, v15 bitop3:0x8e
	v_lshrrev_b32_e32 v12, 31, v12
	v_lshrrev_b32_e32 v13, 31, v13
	v_lshrrev_b32_e32 v14, 31, v14
	v_lshrrev_b32_e32 v15, 31, v15
	v_add3_u32 v10, v10, v12, v13
	v_add3_u32 v11, v11, v14, v15
.Lsel_g0:
	v_sub_u32_e32 v12, v2, v9
	v_sub_u32_e32 v13, v146, v9
	v_sub_u32_e32 v14, v145, v9
	v_sub_u32_e32 v15, v148, v9
	v_bitop3_b32 v12, v2, v9, v12 bitop3:0x8e
	v_bitop3_b32 v13, v146, v9, v13 bitop3:0x8e
	v_bitop3_b32 v14, v145, v9, v14 bitop3:0x8e
	v_bitop3_b32 v15, v148, v9, v15 bitop3:0x8e
	v_lshrrev_b32_e32 v12, 31, v12
	v_lshrrev_b32_e32 v13, 31, v13
	v_lshrrev_b32_e32 v14, 31, v14
	v_lshrrev_b32_e32 v15, 31, v15
	v_add3_u32 v10, v10, v12, v13
	v_add3_u32 v11, v11, v14, v15
	v_sub_u32_e32 v12, v147, v9
	v_sub_u32_e32 v13, v150, v9
	v_sub_u32_e32 v14, v149, v9
	v_sub_u32_e32 v15, v152, v9
	v_bitop3_b32 v12, v147, v9, v12 bitop3:0x8e
	v_bitop3_b32 v13, v150, v9, v13 bitop3:0x8e
	v_bitop3_b32 v14, v149, v9, v14 bitop3:0x8e
	v_bitop3_b32 v15, v152, v9, v15 bitop3:0x8e
	v_lshrrev_b32_e32 v12, 31, v12
	v_lshrrev_b32_e32 v13, 31, v13
	v_lshrrev_b32_e32 v14, 31, v14
	v_lshrrev_b32_e32 v15, 31, v15
	v_add3_u32 v10, v10, v12, v13
	v_add3_u32 v11, v11, v14, v15
	v_add_u32_e32 v10, v10, v11
	v_sub_u32_e32 v10, s72, v10
	ds_bpermute_b32 v11, v4, v10
	s_waitcnt lgkmcnt(0)
	v_add_u32_e32 v10, v10, v11
	s_nop 1
	v_add_u32_dpp v10, v10, v10 quad_perm:[1,0,3,2] row_mask:0xf bank_mask:0xf
	s_nop 1
	v_add_u32_dpp v10, v10, v10 quad_perm:[2,3,0,1] row_mask:0xf bank_mask:0xf
	s_nop 1
	v_add_u32_dpp v10, v10, v10 row_half_mirror row_mask:0xf bank_mask:0xf
	s_nop 1
	v_add_u32_dpp v10, v10, v10 row_mirror row_mask:0xf bank_mask:0xf
	v_cmp_gt_i32_e32 vcc, v10, v3
	s_cmp_eq_u32 s0, -1
	s_nop 0
	v_cndmask_b32_e32 v144, v144, v9, vcc
	s_cbranch_scc0 .LBB0_974
; DI void indexer_phase(const u16* __restrict__ P, unsigned* __restrict__ mask) {
;     ...
; #pragma unroll
;     for (int kb = 0; kb < 64; ++kb) {
;       const bool pred = (sc[kb] >= T) && (sc[kb] != 0u);
;       const unsigned long long bal = __ballot(pred);
;       const unsigned wd = (unsigned)(bal >> (32 * hi));
;       if ((kb & 31) == r32) { if (kb < 32) w0 = wd; else w1 = wd; }
;     }
;     mask[(brow + tme) * 64 + r32] = w0;
;     mask[(brow + tme) * 64 + 32 + r32] = w1;
	v_cmp_ge_u32_e32 vcc, v2, v144
	v_cmp_ne_u32_e64 s[0:1], 0, v2
	s_and_b64 s[0:1], s[0:1], vcc
	v_readlane_b32 s36, v254, 56
	v_cndmask_b32_e64 v2, 0, 1, s[0:1]
	v_cmp_ne_u32_e32 vcc, 0, v2
	v_cmp_ne_u32_e64 s[0:1], 0, v146
	v_readlane_b32 s37, v254, 57
	v_lshrrev_b64 v[2:3], v56, vcc
	v_cmp_ge_u32_e32 vcc, v146, v144
	s_and_b64 s[0:1], s[0:1], vcc
	v_cndmask_b32_e64 v4, 0, v2, s[36:37]
	v_cndmask_b32_e64 v2, 0, 1, s[0:1]
	v_cmp_ne_u32_e32 vcc, 0, v2
	v_readlane_b32 s38, v254, 58
	v_cmp_ne_u32_e64 s[0:1], 0, v145
	v_lshrrev_b64 v[2:3], v56, vcc
	v_cmp_ge_u32_e32 vcc, v145, v144
	v_readlane_b32 s39, v254, 59
	s_and_b64 s[0:1], s[0:1], vcc
	v_readlane_b32 s40, v254, 60
	v_cndmask_b32_e64 v4, v4, v2, s[38:39]
	v_cndmask_b32_e64 v2, 0, 1, s[0:1]
	v_cmp_ne_u32_e32 vcc, 0, v2
	v_cmp_ne_u32_e64 s[0:1], 0, v148
	v_readlane_b32 s41, v254, 61
	v_lshrrev_b64 v[2:3], v56, vcc
	v_cmp_ge_u32_e32 vcc, v148, v144
	s_and_b64 s[0:1], s[0:1], vcc
	v_cndmask_b32_e64 v4, v4, v2, s[40:41]
	v_cndmask_b32_e64 v2, 0, 1, s[0:1]
	v_cmp_ne_u32_e32 vcc, 0, v2
	v_readlane_b32 s44, v254, 62
	v_cmp_ne_u32_e64 s[0:1], 0, v147
	v_lshrrev_b64 v[2:3], v56, vcc
	v_cmp_ge_u32_e32 vcc, v147, v144
	v_readlane_b32 s45, v254, 63
	s_and_b64 s[0:1], s[0:1], vcc
	v_readlane_b32 s46, v255, 0
	v_cndmask_b32_e64 v4, v4, v2, s[44:45]
	v_cndmask_b32_e64 v2, 0, 1, s[0:1]
	v_cmp_ne_u32_e32 vcc, 0, v2
	v_cmp_ne_u32_e64 s[0:1], 0, v150
	v_readlane_b32 s47, v255, 1
	v_lshrrev_b64 v[2:3], v56, vcc
	v_cmp_ge_u32_e32 vcc, v150, v144
	s_and_b64 s[0:1], s[0:1], vcc
	v_cndmask_b32_e64 v4, v4, v2, s[46:47]
	v_cndmask_b32_e64 v2, 0, 1, s[0:1]
	v_cmp_ne_u32_e32 vcc, 0, v2
	v_readlane_b32 s48, v255, 2
	v_cmp_ne_u32_e64 s[0:1], 0, v149
	v_lshrrev_b64 v[2:3], v56, vcc
	v_cmp_ge_u32_e32 vcc, v149, v144
	v_readlane_b32 s49, v255, 3
	s_and_b64 s[0:1], s[0:1], vcc
	v_readlane_b32 s50, v255, 4
	v_cndmask_b32_e64 v4, v4, v2, s[48:49]
	v_cndmask_b32_e64 v2, 0, 1, s[0:1]
	v_cmp_ne_u32_e32 vcc, 0, v2
	v_cmp_ne_u32_e64 s[0:1], 0, v152
	v_readlane_b32 s51, v255, 5
	v_lshrrev_b64 v[2:3], v56, vcc
	v_cmp_ge_u32_e32 vcc, v152, v144
	s_and_b64 s[0:1], s[0:1], vcc
	v_cndmask_b32_e64 v4, v4, v2, s[50:51]
	v_cndmask_b32_e64 v2, 0, 1, s[0:1]
	v_cmp_ne_u32_e32 vcc, 0, v2
	v_readlane_b32 s18, v255, 6
	v_cmp_ne_u32_e64 s[0:1], 0, v151
	v_lshrrev_b64 v[2:3], v56, vcc
	v_cmp_ge_u32_e32 vcc, v151, v144
	v_readlane_b32 s19, v255, 7
	s_and_b64 s[0:1], s[0:1], vcc
	v_readlane_b32 s22, v255, 8
	v_cndmask_b32_e64 v4, v4, v2, s[18:19]
	v_cndmask_b32_e64 v2, 0, 1, s[0:1]
	v_cmp_ne_u32_e32 vcc, 0, v2
	v_cmp_ne_u32_e64 s[0:1], 0, v154
	v_readlane_b32 s23, v255, 9
	v_lshrrev_b64 v[2:3], v56, vcc
	v_cmp_ge_u32_e32 vcc, v154, v144
	s_and_b64 s[0:1], s[0:1], vcc
	v_cndmask_b32_e64 v4, v4, v2, s[22:23]
	v_cndmask_b32_e64 v2, 0, 1, s[0:1]
	v_cmp_ne_u32_e32 vcc, 0, v2
	v_readlane_b32 s24, v255, 10
	v_cmp_ne_u32_e64 s[0:1], 0, v153
	v_lshrrev_b64 v[2:3], v56, vcc
	v_cmp_ge_u32_e32 vcc, v153, v144
	v_readlane_b32 s25, v255, 11
	s_and_b64 s[0:1], s[0:1], vcc
	v_readlane_b32 s26, v255, 12
	v_cndmask_b32_e64 v4, v4, v2, s[24:25]
	v_cndmask_b32_e64 v2, 0, 1, s[0:1]
	v_cmp_ne_u32_e32 vcc, 0, v2
	v_cmp_ne_u32_e64 s[0:1], 0, v156
	v_readlane_b32 s27, v255, 13
	v_lshrrev_b64 v[2:3], v56, vcc
	v_cmp_ge_u32_e32 vcc, v156, v144
	s_and_b64 s[0:1], s[0:1], vcc
	v_cndmask_b32_e64 v4, v4, v2, s[26:27]
	v_cndmask_b32_e64 v2, 0, 1, s[0:1]
	v_cmp_ne_u32_e32 vcc, 0, v2
	v_readlane_b32 s30, v255, 14
	v_cmp_ne_u32_e64 s[0:1], 0, v155
	v_lshrrev_b64 v[2:3], v56, vcc
	v_cmp_ge_u32_e32 vcc, v155, v144
	v_readlane_b32 s31, v255, 15
	s_and_b64 s[0:1], s[0:1], vcc
	v_readlane_b32 s8, v255, 16
	v_cndmask_b32_e64 v4, v4, v2, s[30:31]
	v_cndmask_b32_e64 v2, 0, 1, s[0:1]
	v_cmp_ne_u32_e32 vcc, 0, v2
	v_cmp_ne_u32_e64 s[0:1], 0, v158
	v_readlane_b32 s9, v255, 17
	v_lshrrev_b64 v[2:3], v56, vcc
	v_cmp_ge_u32_e32 vcc, v158, v144
	s_and_b64 s[0:1], s[0:1], vcc
	v_cndmask_b32_e64 v4, v4, v2, s[8:9]
	v_cndmask_b32_e64 v2, 0, 1, s[0:1]
	v_cmp_ne_u32_e32 vcc, 0, v2
	v_readlane_b32 s10, v255, 18
	v_cmp_ne_u32_e64 s[0:1], 0, v157
	v_lshrrev_b64 v[2:3], v56, vcc
	v_cmp_ge_u32_e32 vcc, v157, v144
	v_readlane_b32 s11, v255, 19
	s_and_b64 s[0:1], s[0:1], vcc
	v_readlane_b32 s12, v255, 20
	v_cndmask_b32_e64 v4, v4, v2, s[10:11]
	v_cndmask_b32_e64 v2, 0, 1, s[0:1]
	v_cmp_ne_u32_e32 vcc, 0, v2
	v_cmp_ne_u32_e64 s[0:1], 0, v160
	v_readlane_b32 s13, v255, 21
	v_lshrrev_b64 v[2:3], v56, vcc
	v_cmp_ge_u32_e32 vcc, v160, v144
	s_and_b64 s[0:1], s[0:1], vcc
	v_cndmask_b32_e64 v4, v4, v2, s[12:13]
	v_cndmask_b32_e64 v2, 0, 1, s[0:1]
	v_cmp_ne_u32_e32 vcc, 0, v2
	v_readlane_b32 s14, v255, 22
	v_cmp_ne_u32_e64 s[0:1], 0, v159
	v_lshrrev_b64 v[2:3], v56, vcc
	v_cmp_ge_u32_e32 vcc, v159, v144
	v_readlane_b32 s15, v255, 23
	s_and_b64 s[0:1], s[0:1], vcc
	v_readlane_b32 s66, v255, 24
	v_cndmask_b32_e64 v4, v4, v2, s[14:15]
	v_cndmask_b32_e64 v2, 0, 1, s[0:1]
	v_cmp_ne_u32_e32 vcc, 0, v2
	v_cmp_ne_u32_e64 s[0:1], 0, v162
	v_readlane_b32 s67, v255, 25
	v_lshrrev_b64 v[2:3], v56, vcc
	v_cmp_ge_u32_e32 vcc, v162, v144
	s_and_b64 s[0:1], s[0:1], vcc
	v_cndmask_b32_e64 v4, v4, v2, s[66:67]
	v_cndmask_b32_e64 v2, 0, 1, s[0:1]
	v_cmp_ne_u32_e32 vcc, 0, v2
	v_readlane_b32 s68, v255, 26
	v_cmp_ne_u32_e64 s[0:1], 0, v161
	v_lshrrev_b64 v[2:3], v56, vcc
	v_cmp_ge_u32_e32 vcc, v161, v144
	v_readlane_b32 s69, v255, 27
	s_and_b64 s[0:1], s[0:1], vcc
	v_readlane_b32 s70, v255, 28
	v_cndmask_b32_e64 v4, v4, v2, s[68:69]
	v_cndmask_b32_e64 v2, 0, 1, s[0:1]
	v_cmp_ne_u32_e32 vcc, 0, v2
	v_cmp_ne_u32_e64 s[0:1], 0, v164
	v_readlane_b32 s71, v255, 29
	v_lshrrev_b64 v[2:3], v56, vcc
	v_cmp_ge_u32_e32 vcc, v164, v144
; DI void indexer_phase(const u16* __restrict__ P, unsigned* __restrict__ mask) {
;     ...
; #pragma unroll
;     for (int kb = 0; kb < 64; ++kb) {
;       const bool pred = (sc[kb] >= T) && (sc[kb] != 0u);
;       const unsigned long long bal = __ballot(pred);
;       const unsigned wd = (unsigned)(bal >> (32 * hi));
;       if ((kb & 31) == r32) { if (kb < 32) w0 = wd; else w1 = wd; }
;     }
;     mask[(brow + tme) * 64 + r32] = w0;
;     mask[(brow + tme) * 64 + 32 + r32] = w1;
	s_and_b64 s[0:1], s[0:1], vcc
	v_cndmask_b32_e64 v4, v4, v2, s[70:71]
	v_cndmask_b32_e64 v2, 0, 1, s[0:1]
	v_cmp_ne_u32_e32 vcc, 0, v2
	v_readlane_b32 s72, v255, 30
	v_cmp_ne_u32_e64 s[0:1], 0, v163
	v_lshrrev_b64 v[2:3], v56, vcc
	v_cmp_ge_u32_e32 vcc, v163, v144
	v_readlane_b32 s73, v255, 31
	s_and_b64 s[0:1], s[0:1], vcc
	v_readlane_b32 s42, v255, 32
	v_cndmask_b32_e64 v4, v4, v2, s[72:73]
	v_cndmask_b32_e64 v2, 0, 1, s[0:1]
	v_cmp_ne_u32_e32 vcc, 0, v2
	v_cmp_ne_u32_e64 s[0:1], 0, v166
	v_readlane_b32 s43, v255, 33
	v_lshrrev_b64 v[2:3], v56, vcc
	v_cmp_ge_u32_e32 vcc, v166, v144
	s_and_b64 s[0:1], s[0:1], vcc
	v_cndmask_b32_e64 v4, v4, v2, s[42:43]
	v_cndmask_b32_e64 v2, 0, 1, s[0:1]
	v_cmp_ne_u32_e32 vcc, 0, v2
	v_readlane_b32 s34, v255, 34
	v_cmp_ne_u32_e64 s[0:1], 0, v165
	v_lshrrev_b64 v[2:3], v56, vcc
	v_cmp_ge_u32_e32 vcc, v165, v144
	v_readlane_b32 s35, v255, 35
	s_and_b64 s[0:1], s[0:1], vcc
	v_readlane_b32 s52, v255, 36
	v_cndmask_b32_e64 v4, v4, v2, s[34:35]
	v_cndmask_b32_e64 v2, 0, 1, s[0:1]
	v_cmp_ne_u32_e32 vcc, 0, v2
	v_cmp_ne_u32_e64 s[0:1], 0, v168
	v_readlane_b32 s53, v255, 37
	v_lshrrev_b64 v[2:3], v56, vcc
	v_cmp_ge_u32_e32 vcc, v168, v144
	s_and_b64 s[0:1], s[0:1], vcc
	v_cndmask_b32_e64 v4, v4, v2, s[52:53]
	v_cndmask_b32_e64 v2, 0, 1, s[0:1]
	v_cmp_ne_u32_e32 vcc, 0, v2
	v_readlane_b32 s90, v255, 38
	v_cmp_ne_u32_e64 s[0:1], 0, v167
	v_lshrrev_b64 v[2:3], v56, vcc
	v_cmp_ge_u32_e32 vcc, v167, v144
	v_readlane_b32 s91, v255, 39
	s_and_b64 s[0:1], s[0:1], vcc
	v_readlane_b32 s28, v255, 40
	v_cndmask_b32_e64 v4, v4, v2, s[90:91]
	v_cndmask_b32_e64 v2, 0, 1, s[0:1]
	v_cmp_ne_u32_e32 vcc, 0, v2
	v_cmp_ne_u32_e64 s[0:1], 0, v170
	v_readlane_b32 s29, v255, 41
	v_lshrrev_b64 v[2:3], v56, vcc
	v_cmp_ge_u32_e32 vcc, v170, v144
	s_and_b64 s[0:1], s[0:1], vcc
	v_cndmask_b32_e64 v4, v4, v2, s[28:29]
	v_cndmask_b32_e64 v2, 0, 1, s[0:1]
	v_cmp_ne_u32_e32 vcc, 0, v2
	v_readlane_b32 s54, v255, 42
	v_cmp_ne_u32_e64 s[0:1], 0, v169
	v_lshrrev_b64 v[2:3], v56, vcc
	v_cmp_ge_u32_e32 vcc, v169, v144
	v_readlane_b32 s55, v255, 43
	s_and_b64 s[0:1], s[0:1], vcc
	v_readlane_b32 s94, v255, 44
	v_cndmask_b32_e64 v4, v4, v2, s[54:55]
	v_cndmask_b32_e64 v2, 0, 1, s[0:1]
	v_cmp_ne_u32_e32 vcc, 0, v2
	v_cmp_ne_u32_e64 s[0:1], 0, v172
	v_readlane_b32 s95, v255, 45
	v_lshrrev_b64 v[2:3], v56, vcc
	v_cmp_ge_u32_e32 vcc, v172, v144
	s_and_b64 s[0:1], s[0:1], vcc
	v_cndmask_b32_e64 v4, v4, v2, s[94:95]
	v_cndmask_b32_e64 v2, 0, 1, s[0:1]
	v_cmp_ne_u32_e32 vcc, 0, v2
	v_readlane_b32 s2, v255, 46
	v_cmp_ne_u32_e64 s[0:1], 0, v171
	v_lshrrev_b64 v[2:3], v56, vcc
	v_cmp_ge_u32_e32 vcc, v171, v144
	v_readlane_b32 s3, v255, 47
	s_and_b64 s[0:1], s[0:1], vcc
	v_readlane_b32 s4, v255, 48
	v_cndmask_b32_e64 v4, v4, v2, s[2:3]
	v_cndmask_b32_e64 v2, 0, 1, s[0:1]
	v_cmp_ne_u32_e32 vcc, 0, v2
	v_cmp_ne_u32_e64 s[0:1], 0, v174
	v_readlane_b32 s5, v255, 49
	v_lshrrev_b64 v[2:3], v56, vcc
	v_cmp_ge_u32_e32 vcc, v174, v144
	s_and_b64 s[0:1], s[0:1], vcc
	v_cndmask_b32_e64 v4, v4, v2, s[4:5]
	v_cndmask_b32_e64 v2, 0, 1, s[0:1]
	v_cmp_ne_u32_e32 vcc, 0, v2
	v_readlane_b32 s20, v255, 50
	v_cmp_ne_u32_e64 s[0:1], 0, v173
	v_lshrrev_b64 v[2:3], v56, vcc
	v_cmp_ge_u32_e32 vcc, v173, v144
	v_readlane_b32 s21, v255, 51
	s_and_b64 s[0:1], s[0:1], vcc
	v_readlane_b32 s64, v255, 52
	v_cndmask_b32_e64 v4, v4, v2, s[20:21]
	v_cndmask_b32_e64 v2, 0, 1, s[0:1]
	v_cmp_ne_u32_e32 vcc, 0, v2
	v_cmp_ne_u32_e64 s[0:1], 0, v182
	v_readlane_b32 s65, v255, 53
	v_lshrrev_b64 v[2:3], v56, vcc
	v_cmp_ge_u32_e32 vcc, v182, v144
	s_and_b64 s[0:1], s[0:1], vcc
	v_cndmask_b32_e64 v4, v4, v2, s[64:65]
	v_cndmask_b32_e64 v2, 0, 1, s[0:1]
	v_cmp_ne_u32_e32 vcc, 0, v2
	v_readlane_b32 s74, v255, 54
	v_cmp_ne_u32_e64 s[0:1], 0, v175
	v_lshrrev_b64 v[2:3], v56, vcc
	v_cmp_ge_u32_e32 vcc, v175, v144
	v_readlane_b32 s75, v255, 55
	s_and_b64 s[0:1], s[0:1], vcc
	s_nop 0
	v_cndmask_b32_e64 v4, v4, v2, s[74:75]
	v_cndmask_b32_e64 v2, 0, 1, s[0:1]
	v_cmp_ne_u32_e32 vcc, 0, v2
	v_cmp_ne_u32_e64 s[0:1], 0, v184
	s_nop 0
	v_lshrrev_b64 v[2:3], v56, vcc
	v_cmp_ge_u32_e32 vcc, v184, v144
	s_and_b64 s[0:1], s[0:1], vcc
	v_cndmask_b32_e64 v5, 0, v2, s[36:37]
	v_cndmask_b32_e64 v2, 0, 1, s[0:1]
	v_cmp_ne_u32_e32 vcc, 0, v2
	v_cmp_ne_u32_e64 s[0:1], 0, v183
	s_nop 0
	v_lshrrev_b64 v[2:3], v56, vcc
	v_cmp_ge_u32_e32 vcc, v183, v144
	s_and_b64 s[0:1], s[0:1], vcc
	v_cndmask_b32_e64 v5, v5, v2, s[38:39]
	v_cndmask_b32_e64 v2, 0, 1, s[0:1]
	v_cmp_ne_u32_e32 vcc, 0, v2
	v_cmp_ne_u32_e64 s[0:1], 0, v186
	s_nop 0
	v_lshrrev_b64 v[2:3], v56, vcc
	v_cmp_ge_u32_e32 vcc, v186, v144
	s_and_b64 s[0:1], s[0:1], vcc
	v_cndmask_b32_e64 v5, v5, v2, s[40:41]
	v_cndmask_b32_e64 v2, 0, 1, s[0:1]
	v_cmp_ne_u32_e32 vcc, 0, v2
	v_cmp_ne_u32_e64 s[0:1], 0, v185
	s_nop 0
	v_lshrrev_b64 v[2:3], v56, vcc
	v_cmp_ge_u32_e32 vcc, v185, v144
	s_and_b64 s[0:1], s[0:1], vcc
	v_cndmask_b32_e64 v5, v5, v2, s[44:45]
	v_cndmask_b32_e64 v2, 0, 1, s[0:1]
	v_cmp_ne_u32_e32 vcc, 0, v2
	v_cmp_ne_u32_e64 s[0:1], 0, v188
	s_nop 0
	v_lshrrev_b64 v[2:3], v56, vcc
	v_cmp_ge_u32_e32 vcc, v188, v144
	s_and_b64 s[0:1], s[0:1], vcc
	v_cndmask_b32_e64 v5, v5, v2, s[46:47]
	v_cndmask_b32_e64 v2, 0, 1, s[0:1]
	v_cmp_ne_u32_e32 vcc, 0, v2
	v_cmp_ne_u32_e64 s[0:1], 0, v187
	s_nop 0
	v_lshrrev_b64 v[2:3], v56, vcc
	v_cmp_ge_u32_e32 vcc, v187, v144
	s_and_b64 s[0:1], s[0:1], vcc
	v_cndmask_b32_e64 v5, v5, v2, s[48:49]
	v_cndmask_b32_e64 v2, 0, 1, s[0:1]
	v_cmp_ne_u32_e32 vcc, 0, v2
	v_cmp_ne_u32_e64 s[0:1], 0, v190
	s_nop 0
	v_lshrrev_b64 v[2:3], v56, vcc
	v_cmp_ge_u32_e32 vcc, v190, v144
	s_and_b64 s[0:1], s[0:1], vcc
	v_cndmask_b32_e64 v5, v5, v2, s[50:51]
; DI void indexer_phase(const u16* __restrict__ P, unsigned* __restrict__ mask) {
;     ...
; #pragma unroll
;     for (int kb = 0; kb < 64; ++kb) {
;       const bool pred = (sc[kb] >= T) && (sc[kb] != 0u);
;       const unsigned long long bal = __ballot(pred);
;       const unsigned wd = (unsigned)(bal >> (32 * hi));
;       if ((kb & 31) == r32) { if (kb < 32) w0 = wd; else w1 = wd; }
;     }
;     mask[(brow + tme) * 64 + r32] = w0;
;     mask[(brow + tme) * 64 + 32 + r32] = w1;
	v_cndmask_b32_e64 v2, 0, 1, s[0:1]
	v_cmp_ne_u32_e32 vcc, 0, v2
	v_cmp_ne_u32_e64 s[0:1], 0, v189
	s_nop 0
	v_lshrrev_b64 v[2:3], v56, vcc
	v_cmp_ge_u32_e32 vcc, v189, v144
	s_and_b64 s[0:1], s[0:1], vcc
	v_cndmask_b32_e64 v5, v5, v2, s[18:19]
	v_cndmask_b32_e64 v2, 0, 1, s[0:1]
	v_cmp_ne_u32_e32 vcc, 0, v2
	v_cmp_ne_u32_e64 s[0:1], 0, v192
	s_nop 0
	v_lshrrev_b64 v[2:3], v56, vcc
	v_cmp_ge_u32_e32 vcc, v192, v144
	s_and_b64 s[0:1], s[0:1], vcc
	v_cndmask_b32_e64 v5, v5, v2, s[22:23]
	v_cndmask_b32_e64 v2, 0, 1, s[0:1]
	v_cmp_ne_u32_e32 vcc, 0, v2
	v_cmp_ne_u32_e64 s[0:1], 0, v191
	s_nop 0
	v_lshrrev_b64 v[2:3], v56, vcc
	v_cmp_ge_u32_e32 vcc, v191, v144
	s_and_b64 s[0:1], s[0:1], vcc
	v_cndmask_b32_e64 v5, v5, v2, s[24:25]
	v_cndmask_b32_e64 v2, 0, 1, s[0:1]
	v_cmp_ne_u32_e32 vcc, 0, v2
	v_cmp_ne_u32_e64 s[0:1], 0, v194
	s_nop 0
	v_lshrrev_b64 v[2:3], v56, vcc
	v_cmp_ge_u32_e32 vcc, v194, v144
	s_and_b64 s[0:1], s[0:1], vcc
	v_cndmask_b32_e64 v5, v5, v2, s[26:27]
	v_cndmask_b32_e64 v2, 0, 1, s[0:1]
	v_cmp_ne_u32_e32 vcc, 0, v2
	v_cmp_ne_u32_e64 s[0:1], 0, v193
	s_nop 0
	v_lshrrev_b64 v[2:3], v56, vcc
	v_cmp_ge_u32_e32 vcc, v193, v144
	s_and_b64 s[0:1], s[0:1], vcc
	v_cndmask_b32_e64 v5, v5, v2, s[30:31]
	v_cndmask_b32_e64 v2, 0, 1, s[0:1]
	v_cmp_ne_u32_e32 vcc, 0, v2
	v_cmp_ne_u32_e64 s[0:1], 0, v196
	s_nop 0
	v_lshrrev_b64 v[2:3], v56, vcc
	v_cmp_ge_u32_e32 vcc, v196, v144
	s_and_b64 s[0:1], s[0:1], vcc
	v_cndmask_b32_e64 v5, v5, v2, s[8:9]
	v_cndmask_b32_e64 v2, 0, 1, s[0:1]
	v_cmp_ne_u32_e32 vcc, 0, v2
	v_cmp_ne_u32_e64 s[0:1], 0, v195
	v_readlane_b32 s8, v255, 56
	v_lshrrev_b64 v[2:3], v56, vcc
	v_cmp_ge_u32_e32 vcc, v195, v144
	s_and_b64 s[0:1], s[0:1], vcc
	v_cndmask_b32_e64 v5, v5, v2, s[10:11]
	v_cndmask_b32_e64 v2, 0, 1, s[0:1]
	v_cmp_ne_u32_e32 vcc, 0, v2
	v_cmp_ne_u32_e64 s[0:1], 0, v198
	v_readlane_b32 s9, v255, 57
	v_lshrrev_b64 v[2:3], v56, vcc
	v_cmp_ge_u32_e32 vcc, v198, v144
	s_and_b64 s[0:1], s[0:1], vcc
	v_cndmask_b32_e64 v5, v5, v2, s[12:13]
	v_cndmask_b32_e64 v2, 0, 1, s[0:1]
	v_cmp_ne_u32_e32 vcc, 0, v2
	v_cmp_ne_u32_e64 s[0:1], 0, v197
	s_nop 0
	v_lshrrev_b64 v[2:3], v56, vcc
	v_cmp_ge_u32_e32 vcc, v197, v144
	s_and_b64 s[0:1], s[0:1], vcc
	v_cndmask_b32_e64 v5, v5, v2, s[14:15]
	v_cndmask_b32_e64 v2, 0, 1, s[0:1]
	v_cmp_ne_u32_e32 vcc, 0, v2
	v_cmp_ne_u32_e64 s[0:1], 0, v200
	s_nop 0
	v_lshrrev_b64 v[2:3], v56, vcc
	v_cmp_ge_u32_e32 vcc, v200, v144
	s_and_b64 s[0:1], s[0:1], vcc
	v_cndmask_b32_e64 v5, v5, v2, s[66:67]
	v_cndmask_b32_e64 v2, 0, 1, s[0:1]
	v_cmp_ne_u32_e32 vcc, 0, v2
	v_cmp_ne_u32_e64 s[0:1], 0, v199
	s_nop 0
	v_lshrrev_b64 v[2:3], v56, vcc
	v_cmp_ge_u32_e32 vcc, v199, v144
	s_and_b64 s[0:1], s[0:1], vcc
	v_cndmask_b32_e64 v5, v5, v2, s[68:69]
	v_cndmask_b32_e64 v2, 0, 1, s[0:1]
	v_cmp_ne_u32_e32 vcc, 0, v2
	v_cmp_ne_u32_e64 s[0:1], 0, v202
	s_nop 0
	v_lshrrev_b64 v[2:3], v56, vcc
	v_cmp_ge_u32_e32 vcc, v202, v144
	s_and_b64 s[0:1], s[0:1], vcc
	v_cndmask_b32_e64 v5, v5, v2, s[70:71]
	v_cndmask_b32_e64 v2, 0, 1, s[0:1]
	v_cmp_ne_u32_e32 vcc, 0, v2
	v_cmp_ne_u32_e64 s[0:1], 0, v201
	s_nop 0
	v_lshrrev_b64 v[2:3], v56, vcc
	v_cmp_ge_u32_e32 vcc, v201, v144
	s_and_b64 s[0:1], s[0:1], vcc
	v_cndmask_b32_e64 v5, v5, v2, s[72:73]
	v_cndmask_b32_e64 v2, 0, 1, s[0:1]
	v_cmp_ne_u32_e32 vcc, 0, v2
	v_cmp_ne_u32_e64 s[0:1], 0, v204
	s_nop 0
	v_lshrrev_b64 v[2:3], v56, vcc
	v_cmp_ge_u32_e32 vcc, v204, v144
	s_and_b64 s[0:1], s[0:1], vcc
	v_cndmask_b32_e64 v5, v5, v2, s[42:43]
	v_cndmask_b32_e64 v2, 0, 1, s[0:1]
	v_cmp_ne_u32_e32 vcc, 0, v2
	v_cmp_ne_u32_e64 s[0:1], 0, v203
	s_mov_b64 s[42:43], s[76:77]
	v_lshrrev_b64 v[2:3], v56, vcc
	v_cmp_ge_u32_e32 vcc, v203, v144
	s_and_b64 s[0:1], s[0:1], vcc
	v_cndmask_b32_e64 v5, v5, v2, s[34:35]
	v_cndmask_b32_e64 v2, 0, 1, s[0:1]
	v_cmp_ne_u32_e32 vcc, 0, v2
	v_cmp_ne_u32_e64 s[0:1], 0, v206
	v_readlane_b32 s76, v254, 37
	v_lshrrev_b64 v[2:3], v56, vcc
	v_cmp_ge_u32_e32 vcc, v206, v144
	s_and_b64 s[0:1], s[0:1], vcc
	v_cndmask_b32_e64 v5, v5, v2, s[52:53]
	v_cndmask_b32_e64 v2, 0, 1, s[0:1]
	v_cmp_ne_u32_e32 vcc, 0, v2
	v_cmp_ne_u32_e64 s[0:1], 0, v205
	s_mov_b64 s[52:53], s[96:97]
	v_lshrrev_b64 v[2:3], v56, vcc
	v_cmp_ge_u32_e32 vcc, v205, v144
	s_and_b64 s[0:1], s[0:1], vcc
	v_cndmask_b32_e64 v5, v5, v2, s[90:91]
	v_cndmask_b32_e64 v2, 0, 1, s[0:1]
	v_cmp_ne_u32_e32 vcc, 0, v2
	v_cmp_ne_u32_e64 s[0:1], 0, v236
	v_readlane_b32 s96, v254, 33
	v_lshrrev_b64 v[2:3], v56, vcc
	v_cmp_ge_u32_e32 vcc, v236, v144
	s_and_b64 s[0:1], s[0:1], vcc
	v_cndmask_b32_e64 v5, v5, v2, s[28:29]
	v_cndmask_b32_e64 v2, 0, 1, s[0:1]
	v_cmp_ne_u32_e32 vcc, 0, v2
	v_cmp_ne_u32_e64 s[0:1], 0, v207
	v_readlane_b32 s77, v254, 38
	v_lshrrev_b64 v[2:3], v56, vcc
	v_cmp_ge_u32_e32 vcc, v207, v144
	s_and_b64 s[0:1], s[0:1], vcc
	v_cndmask_b32_e64 v5, v5, v2, s[54:55]
	v_cndmask_b32_e64 v2, 0, 1, s[0:1]
	v_cmp_ne_u32_e32 vcc, 0, v2
	v_cmp_ne_u32_e64 s[0:1], 0, v238
	s_movk_i32 s34, 0xc00
	v_lshrrev_b64 v[2:3], v56, vcc
	v_cmp_ge_u32_e32 vcc, v238, v144
	s_and_b64 s[0:1], s[0:1], vcc
	v_cndmask_b32_e64 v5, v5, v2, s[94:95]
	v_cndmask_b32_e64 v2, 0, 1, s[0:1]
	v_cmp_ne_u32_e32 vcc, 0, v2
	v_cmp_ne_u32_e64 s[0:1], 0, v237
	s_mov_b64 s[90:91], s[16:17]
	v_lshrrev_b64 v[2:3], v56, vcc
	v_cmp_ge_u32_e32 vcc, v237, v144
	s_and_b64 s[0:1], s[0:1], vcc
	v_cndmask_b32_e64 v5, v5, v2, s[2:3]
	v_cndmask_b32_e64 v2, 0, 1, s[0:1]
	v_cmp_ne_u32_e32 vcc, 0, v2
	v_cmp_ne_u32_e64 s[0:1], 0, v240
	s_mov_b32 s28, s78
	v_lshrrev_b64 v[2:3], v56, vcc
	v_cmp_ge_u32_e32 vcc, v240, v144
	s_and_b64 s[0:1], s[0:1], vcc
	v_cndmask_b32_e64 v5, v5, v2, s[4:5]
	v_cndmask_b32_e64 v2, 0, 1, s[0:1]
	v_cmp_ne_u32_e32 vcc, 0, v2
	v_cmp_ne_u32_e64 s[0:1], 0, v239
	s_mov_b64 s[4:5], s[84:85]
	v_lshrrev_b64 v[2:3], v56, vcc
	v_cmp_ge_u32_e32 vcc, v239, v144
	s_and_b64 s[0:1], s[0:1], vcc
	v_cndmask_b32_e64 v5, v5, v2, s[20:21]
	v_cndmask_b32_e64 v2, 0, 1, s[0:1]
	v_cmp_ne_u32_e32 vcc, 0, v2
	v_cmp_ne_u32_e64 s[0:1], 0, v18
	v_readlane_b32 s97, v254, 34
	v_lshrrev_b64 v[2:3], v56, vcc
	v_cmp_ge_u32_e32 vcc, v18, v144
	s_and_b64 s[0:1], s[0:1], vcc
	v_cndmask_b32_e64 v5, v5, v2, s[64:65]
	v_cndmask_b32_e64 v2, 0, 1, s[0:1]
	v_cmp_ne_u32_e32 vcc, 0, v2
	s_mov_b32 s35, s86
	s_mov_b32 s84, s79
	v_lshrrev_b64 v[2:3], v56, vcc
	v_cndmask_b32_e64 v5, v5, v2, s[74:75]
	v_add_u32_e32 v2, v127, v126
	v_mov_b32_e32 v3, v1
	v_lshlrev_b64 v[2:3], 8, v[2:3]
	v_readlane_b32 s74, v254, 35
	v_lshl_add_u64 v[2:3], v[58:59], 0, v[2:3]
	v_readlane_b32 s75, v254, 36
	s_mov_b32 s55, s59
	s_mov_b32 s3, s63
	s_movk_i32 s20, 0x600
	s_mov_b32 s21, 0x41000000
	s_mov_b32 s64, 0x3e38aa3b
	s_movk_i32 s2, 0x2000
	global_store_dword v[2:3], v4, off
	global_store_dword v[2:3], v5, off offset:128
	s_branch .LBB0_845
